# b1 slice of the idle copy moved to P3's last round; split-K last-arriver epilogues of P2 and P9 issue the 4 residual loads of a 16-row group together (counted waits, store-data wait states kept)
# speedup vs baseline: 1.0272x; 1.0030x over previous
; __device__ __forceinline__ void copy_slice(KParams P, unsigned lo, unsigned hi, unsigned t0, unsigned nthr) {
;     if (lo < CP_S0 && hi > 0) copy_seg<128, 256>(P->in[2], P->out + O_AS, lo, hi < CP_S0 ? hi : CP_S0, t0, nthr);
;     if (lo < CP_S1 && hi > CP_S0) copy_seg<128, 512>(P->in[3], P->out + O_B1S, (lo > CP_S0 ? lo : CP_S0) - CP_S0, (hi < CP_S1 ? hi : CP_S1) - CP_S0, t0, nthr);
; __global__ void __launch_bounds__(512, 2) mega_fwd(Params Parg) {
;     ...
;       if (bgr) { idle_copy(P, 129 * 22, 0u, CP_S1, wave_sg); idle_copy(P, 129 * 22, CP_S1 + B2_C1, CP_S2, wave_sg); } }
.LBB0_276:
	s_or_b64 exec, exec, s[12:13]
	s_branch .LBB0_283

; #define PG8_LAS __attribute__((address_space(3)))
; #define PG8_BAR __builtin_amdgcn_s_barrier()
; template <class Epi, class Sched, bool ALIGN_EPI = false, bool SP2 = false, class Bg = BgNone>
; __device__ __forceinline__ void gemm_phase(PG8_LAS unsigned char* lds, const Gemm g, const Sched& S, const Epi& E, const int wave_sg, const Bg& bg = Bg()) {
;     ...
;             PG8_LAS unsigned* flag = (PG8_LAS unsigned*)(lds + STAGE_BYTES);
;             PG8_BAR;
;             if (tid == 0) { const unsigned old = __hip_atomic_fetch_add(S.cnt + cur.pn, 1u, __ATOMIC_ACQ_REL, __HIP_MEMORY_SCOPE_AGENT); *flag = (old == (unsigned)cur.split - 1u) ? 1u : 0u; }
;             asm volatile("s_waitcnt lgkmcnt(0)" ::: "memory"); PG8_BAR; asm volatile("" ::: "memory");
;             const bool lastone = *flag != 0u;
;             asm volatile("s_waitcnt lgkmcnt(0)" ::: "memory"); PG8_BAR;
;             if (lastone) { __threadfence();
; #pragma unroll
;                 for (int m = 0; m < 4; ++m)
; #pragma unroll
;                     for (int bj = 0; bj < 2; ++bj)
; #pragma unroll
;                         for (int n = 0; n < 2; ++n) {
; #pragma unroll
;                             for (int c = 0; c < 4; ++c) acc[0][bj][m][n][c] = __hip_atomic_load(ab + (((m * 2 + bj) * 2 + n) * 4 + c) * 512, __ATOMIC_RELAXED, __HIP_MEMORY_SCOPE_AGENT);
.LBB0_454:
	s_or_b64 exec, exec, s[0:1]
	s_mov_b64 s[0:1], 0x1000
	v_lshl_add_u64 v[6:7], v[42:43], 0, s[0:1]
	s_mov_b64 s[0:1], 0x1800
	v_lshl_add_u64 v[8:9], v[42:43], 0, s[0:1]
	s_mov_b64 s[0:1], 0x2000
	v_lshl_add_u64 v[10:11], v[42:43], 0, s[0:1]
	s_mov_b64 s[0:1], 0x2800
	v_lshl_add_u64 v[12:13], v[42:43], 0, s[0:1]
	s_mov_b64 s[0:1], 0x3000
	v_lshl_add_u64 v[14:15], v[42:43], 0, s[0:1]
	s_mov_b64 s[0:1], 0x3800
	v_lshl_add_u64 v[16:17], v[42:43], 0, s[0:1]
	s_mov_b64 s[0:1], 0x4000
	v_lshl_add_u64 v[18:19], v[42:43], 0, s[0:1]
	s_mov_b64 s[0:1], 0x4800
	v_lshl_add_u64 v[20:21], v[42:43], 0, s[0:1]
	s_mov_b64 s[0:1], 0x5000
	v_lshl_add_u64 v[22:23], v[42:43], 0, s[0:1]
	s_mov_b64 s[0:1], 0x5800
	v_lshl_add_u64 v[24:25], v[42:43], 0, s[0:1]
	s_mov_b64 s[0:1], 0x6000
	v_lshl_add_u64 v[26:27], v[42:43], 0, s[0:1]
	s_mov_b64 s[0:1], 0x6800
	v_lshl_add_u64 v[28:29], v[42:43], 0, s[0:1]
	s_mov_b64 s[0:1], 0x7000
	v_lshl_add_u64 v[30:31], v[42:43], 0, s[0:1]
	s_mov_b64 s[0:1], 0x7800
	v_lshl_add_u64 v[32:33], v[42:43], 0, s[0:1]
	s_mov_b64 s[0:1], 0x8000
	v_lshl_add_u64 v[34:35], v[42:43], 0, s[0:1]
	s_mov_b64 s[0:1], 0x8800
	v_lshl_add_u64 v[36:37], v[42:43], 0, s[0:1]
	s_mov_b64 s[0:1], 0x9000
	v_lshl_add_u64 v[38:39], v[42:43], 0, s[0:1]
	s_mov_b64 s[0:1], 0x9800
	v_lshl_add_u64 v[40:41], v[42:43], 0, s[0:1]
	s_mov_b64 s[0:1], 0xa000
	v_lshl_add_u64 v[44:45], v[42:43], 0, s[0:1]
	s_mov_b64 s[0:1], 0xa800
	v_lshl_add_u64 v[46:47], v[42:43], 0, s[0:1]
	s_mov_b64 s[0:1], 0xb000
	v_lshl_add_u64 v[48:49], v[42:43], 0, s[0:1]
	s_mov_b64 s[0:1], 0xb800
	v_lshl_add_u64 v[74:75], v[42:43], 0, s[0:1]
	s_mov_b64 s[0:1], 0xc000
	v_lshl_add_u64 v[76:77], v[42:43], 0, s[0:1]
	s_mov_b64 s[0:1], 0xc800
	v_lshl_add_u64 v[78:79], v[42:43], 0, s[0:1]
	s_mov_b64 s[0:1], 0xd000
	v_lshl_add_u64 v[80:81], v[42:43], 0, s[0:1]
	s_mov_b64 s[0:1], 0xd800
	v_lshl_add_u64 v[82:83], v[42:43], 0, s[0:1]
	s_mov_b64 s[0:1], 0xe000
	v_lshl_add_u64 v[84:85], v[42:43], 0, s[0:1]
	s_mov_b64 s[0:1], 0xe800
	v_lshl_add_u64 v[86:87], v[42:43], 0, s[0:1]
	s_mov_b64 s[0:1], 0xf000
	v_lshl_add_u64 v[88:89], v[42:43], 0, s[0:1]
	s_mov_b64 s[0:1], 0xf800
	v_lshl_add_u64 v[90:91], v[42:43], 0, s[0:1]
	s_mov_b64 s[0:1], 0x10000
	v_lshl_add_u64 v[92:93], v[42:43], 0, s[0:1]
	s_mov_b64 s[0:1], 0x10800
	v_lshl_add_u64 v[94:95], v[42:43], 0, s[0:1]
	s_mov_b64 s[0:1], 0x11000
	v_lshl_add_u64 v[96:97], v[42:43], 0, s[0:1]
	s_mov_b64 s[0:1], 0x11800
	v_lshl_add_u64 v[98:99], v[42:43], 0, s[0:1]
	s_mov_b64 s[0:1], 0x12000
	v_lshl_add_u64 v[100:101], v[42:43], 0, s[0:1]
	s_mov_b64 s[0:1], 0x12800
	v_lshl_add_u64 v[102:103], v[42:43], 0, s[0:1]
	s_mov_b64 s[0:1], 0x13000
	v_lshl_add_u64 v[104:105], v[42:43], 0, s[0:1]
	s_mov_b64 s[0:1], 0x13800
	v_lshl_add_u64 v[106:107], v[42:43], 0, s[0:1]
	s_mov_b64 s[0:1], 0x14000
	v_lshl_add_u64 v[108:109], v[42:43], 0, s[0:1]
	s_mov_b64 s[0:1], 0x14800
	v_lshl_add_u64 v[110:111], v[42:43], 0, s[0:1]
	s_mov_b64 s[0:1], 0x15000
	v_lshl_add_u64 v[112:113], v[42:43], 0, s[0:1]
	s_mov_b64 s[0:1], 0x15800
	v_lshl_add_u64 v[114:115], v[42:43], 0, s[0:1]
	s_mov_b64 s[0:1], 0x16000
	v_lshl_add_u64 v[116:117], v[42:43], 0, s[0:1]
	s_mov_b64 s[0:1], 0x16800
	v_lshl_add_u64 v[118:119], v[42:43], 0, s[0:1]
	s_mov_b64 s[0:1], 0x17000
	v_lshl_add_u64 v[120:121], v[42:43], 0, s[0:1]
	s_mov_b64 s[0:1], 0x17800
	v_lshl_add_u64 v[122:123], v[42:43], 0, s[0:1]
	s_mov_b64 s[0:1], 0x18000
	v_lshl_add_u64 v[124:125], v[42:43], 0, s[0:1]
	s_mov_b64 s[0:1], 0x18800
	v_lshl_add_u64 v[126:127], v[42:43], 0, s[0:1]
	s_mov_b64 s[0:1], 0x19000
	v_lshl_add_u64 v[128:129], v[42:43], 0, s[0:1]
	s_mov_b64 s[0:1], 0x19800
	v_lshl_add_u64 v[130:131], v[42:43], 0, s[0:1]
	s_mov_b64 s[0:1], 0x1a000
	v_lshl_add_u64 v[132:133], v[42:43], 0, s[0:1]
	s_mov_b64 s[0:1], 0x1a800
	v_lshl_add_u64 v[134:135], v[42:43], 0, s[0:1]
	s_mov_b64 s[0:1], 0x1b000
	v_lshl_add_u64 v[136:137], v[42:43], 0, s[0:1]
	s_mov_b64 s[0:1], 0x1b800
	v_lshl_add_u64 v[138:139], v[42:43], 0, s[0:1]
	s_mov_b64 s[0:1], 0x1c000
	v_lshl_add_u64 v[140:141], v[42:43], 0, s[0:1]
	s_mov_b64 s[0:1], 0x1c800
	s_waitcnt lgkmcnt(0)
	s_barrier
	v_mov_b32_e32 v0, s86
	v_lshl_add_u64 v[142:143], v[42:43], 0, s[0:1]
	s_mov_b64 s[0:1], 0x1d000
	ds_read_b32 v0, v0
	v_lshl_add_u64 v[144:145], v[42:43], 0, s[0:1]
	s_mov_b64 s[0:1], 0x1d800
	v_lshl_add_u64 v[146:147], v[42:43], 0, s[0:1]
	s_mov_b64 s[0:1], 0x1e000
	v_lshl_add_u64 v[148:149], v[42:43], 0, s[0:1]
	s_mov_b64 s[0:1], 0x1e800
	v_lshl_add_u64 v[150:151], v[42:43], 0, s[0:1]
	s_mov_b64 s[0:1], 0x1f000
	s_waitcnt lgkmcnt(0)
	v_lshl_add_u64 v[152:153], v[42:43], 0, s[0:1]
	s_mov_b64 s[0:1], 0x1f800
	s_waitcnt lgkmcnt(0)
	v_cmp_eq_u32_e32 vcc, 0, v0
	v_lshl_add_u64 v[154:155], v[42:43], 0, s[0:1]
	s_barrier
	s_cbranch_vccnz .LBB0_516
; __device__ __forceinline__ unsigned cvt_pk_bf16(float lo, float hi) { unsigned r; asm volatile("v_cvt_pk_bf16_f32 %0, %1, %2" : "=v"(r) : "v"(lo), "v"(hi)); return r; }
; template <class Epi, class Sched, bool ALIGN_EPI = false, bool SP2 = false, class Bg = BgNone>
; __device__ __forceinline__ void gemm_phase(PG8_LAS unsigned char* lds, const Gemm g, const Sched& S, const Epi& E, const int wave_sg, const Bg& bg = Bg()) {
;     ...
;             if (lastone) { __threadfence();
; #pragma unroll
;                 for (int m = 0; m < 4; ++m)
; #pragma unroll
;                     for (int bj = 0; bj < 2; ++bj)
; #pragma unroll
;                         for (int n = 0; n < 2; ++n) {
; #pragma unroll
;                             for (int c = 0; c < 4; ++c) acc[0][bj][m][n][c] = __hip_atomic_load(ab + (((m * 2 + bj) * 2 + n) * 4 + c) * 512, __ATOMIC_RELAXED, __HIP_MEMORY_SCOPE_AGENT);
;     __device__ __forceinline__ void operator()(const f32x4 (&acc)[2][2][4][2], const pg8::Unit& u, int wr, int wc, int fr, int fq) const {
;     ...
;             for (int m = 0; m < 4; ++m) { const int row = row0 + ai * 128 + m * 16;
;                 if (row < MV) {
;                     const float* rp = (row < MPR) ? res_p + (size_t)row * DM : res_s + (size_t)(row - MPR) * DM;
;                     float s = 0.f;
; #pragma unroll
;                     for (int bj = 0; bj < 2; ++bj)
; #pragma unroll
;                         for (int n = 0; n < 2; ++n) { const int col = col0 + bj * 128 + n * 16; f32x4 r;
;                             if (RESB) { const u32x2 rw = *(const u32x2*)(resb + (size_t)row * DM + col); r = (f32x4){bf2f(rw.x & 0xffff), bf2f(rw.x >> 16), bf2f(rw.y & 0xffff), bf2f(rw.y >> 16)}; }
;                             else r = *(const f32x4*)(rp + col);
;                             const f32x4 v = r + acc[ai][bj][m][n] * scale;
;                             if (OUTF) *(f32x4*)(out + (size_t)row * DM + col) = v;
;                             else { u32x2 w; w.x = cvt_pk_bf16(v[0], v[1]); w.y = cvt_pk_bf16(v[2], v[3]); *(u32x2*)(outb + (size_t)row * DM + col) = w;
;                                 s += (v[0] * v[0] + v[1] * v[1]) + (v[2] * v[2] + v[3] * v[3]); } }
;                     if (!OUTF) { s += __shfl_xor(s, 16); s += __shfl_xor(s, 32); if (fq == 0) atomicAdd(ss + row, s); }
	buffer_wbl2 sc1
	buffer_inv sc1
	global_load_dword v70, v[42:43], off sc1
	global_load_dword v71, v[42:43], off offset:2048 sc1
	global_load_dword v72, v[6:7], off sc1
	global_load_dword v73, v[8:9], off sc1
	global_load_dword v66, v[10:11], off sc1
	global_load_dword v67, v[12:13], off sc1
	global_load_dword v68, v[14:15], off sc1
	global_load_dword v69, v[16:17], off sc1
	global_load_dword v62, v[18:19], off sc1
	global_load_dword v63, v[20:21], off sc1
	global_load_dword v64, v[22:23], off sc1
	global_load_dword v65, v[24:25], off sc1
	global_load_dword v58, v[26:27], off sc1
	global_load_dword v59, v[28:29], off sc1
	global_load_dword v60, v[30:31], off sc1
	global_load_dword v61, v[32:33], off sc1
	global_load_dword v54, v[34:35], off sc1
	global_load_dword v55, v[36:37], off sc1
	global_load_dword v56, v[38:39], off sc1
	global_load_dword v57, v[40:41], off sc1
	global_load_dword v50, v[44:45], off sc1
	global_load_dword v51, v[46:47], off sc1
	global_load_dword v52, v[48:49], off sc1
	global_load_dword v53, v[74:75], off sc1
	s_nop 0
	global_load_dword v46, v[76:77], off sc1
	global_load_dword v47, v[78:79], off sc1
	global_load_dword v48, v[80:81], off sc1
	global_load_dword v49, v[82:83], off sc1
	global_load_dword v42, v[84:85], off sc1
	global_load_dword v43, v[86:87], off sc1
	global_load_dword v44, v[88:89], off sc1
	global_load_dword v45, v[90:91], off sc1
	global_load_dword v38, v[92:93], off sc1
	global_load_dword v39, v[94:95], off sc1
	global_load_dword v40, v[96:97], off sc1
	global_load_dword v41, v[98:99], off sc1
	global_load_dword v34, v[100:101], off sc1
	global_load_dword v35, v[102:103], off sc1
	global_load_dword v36, v[104:105], off sc1
	global_load_dword v37, v[106:107], off sc1
	global_load_dword v30, v[108:109], off sc1
	global_load_dword v31, v[110:111], off sc1
	global_load_dword v32, v[112:113], off sc1
	global_load_dword v33, v[114:115], off sc1
	global_load_dword v26, v[116:117], off sc1
	global_load_dword v27, v[118:119], off sc1
	global_load_dword v28, v[120:121], off sc1
	global_load_dword v29, v[122:123], off sc1
	global_load_dword v22, v[124:125], off sc1
	global_load_dword v23, v[126:127], off sc1
	global_load_dword v24, v[128:129], off sc1
	global_load_dword v25, v[130:131], off sc1
	global_load_dword v18, v[132:133], off sc1
	global_load_dword v19, v[134:135], off sc1
	global_load_dword v20, v[136:137], off sc1
	global_load_dword v21, v[138:139], off sc1
	global_load_dword v14, v[140:141], off sc1
	global_load_dword v15, v[142:143], off sc1
	global_load_dword v16, v[144:145], off sc1
	global_load_dword v17, v[146:147], off sc1
	global_load_dword v10, v[148:149], off sc1
	global_load_dword v11, v[150:151], off sc1
	global_load_dword v12, v[152:153], off sc1
	global_load_dword v13, v[154:155], off sc1
	v_lshl_add_u32 v8, s94, 8, v230
	v_lshl_or_b32 v6, s44, 8, v233
	v_cmp_gt_i32_e32 vcc, s76, v8
	s_and_saveexec_b64 s[0:1], vcc
	s_cbranch_execz .LBB0_462
	v_cmp_lt_i32_e32 vcc, s77, v8
	s_and_saveexec_b64 s[6:7], vcc
	s_xor_b64 s[6:7], exec, s[6:7]
	v_add_u32_e32 v0, 0xffff8000, v8
	v_lshlrev_b64 v[74:75], 12, v[0:1]
	v_lshl_add_u64 v[74:75], s[18:19], 0, v[74:75]
	v_mov_b32_e32 v9, v1
	s_andn2_saveexec_b64 s[6:7], s[6:7]
	v_ashrrev_i32_e32 v9, 31, v8
	v_lshlrev_b64 v[74:75], 12, v[8:9]
	v_lshl_add_u64 v[74:75], s[16:17], 0, v[74:75]
	s_or_b64 exec, exec, s[6:7]
	v_ashrrev_i32_e32 v7, 31, v6
	v_lshl_add_u64 v[78:79], v[6:7], 2, v[74:75]
	global_load_dwordx4 v[74:77], v[78:79], off
	global_load_dwordx4 v[100:103], v[78:79], off offset:64
	global_load_dwordx4 v[104:107], v[78:79], off offset:512
	global_load_dwordx4 v[108:111], v[78:79], off offset:576
	v_lshlrev_b64 v[80:81], 11, v[8:9]
	v_lshl_add_u64 v[80:81], s[28:29], 0, v[80:81]
	v_lshl_add_u64 v[80:81], v[6:7], 1, v[80:81]
	v_and_b32_e32 v7, 64, v236
	v_xor_b32_e32 v0, 16, v236
	v_add_u32_e32 v7, 64, v7
	v_cmp_lt_i32_e32 vcc, v0, v7
	s_waitcnt vmcnt(3)
	s_nop 1
	v_pk_fma_f32 v[76:77], v[72:73], 0.5, v[76:77] op_sel_hi:[1,0,1]
	v_pk_fma_f32 v[74:75], v[70:71], 0.5, v[74:75] op_sel_hi:[1,0,1]
	v_cndmask_b32_e32 v0, v236, v0, vcc
	v_cvt_pk_bf16_f32 v70, v74, v75
	v_cvt_pk_bf16_f32 v71, v76, v77
	global_store_dwordx2 v[80:81], v[70:71], off
	v_mul_f32_e32 v75, v75, v75
	v_mul_f32_e32 v77, v77, v77
	v_fmac_f32_e32 v75, v74, v74
	v_fmac_f32_e32 v77, v76, v76
	v_add_f32_e32 v74, v75, v77
	v_lshlrev_b32_e32 v0, 2, v0
	s_waitcnt vmcnt(3)
	s_nop 1
	v_pk_fma_f32 v[72:73], v[68:69], 0.5, v[102:103] op_sel_hi:[1, 0, 1]
	v_pk_fma_f32 v[70:71], v[66:67], 0.5, v[100:101] op_sel_hi:[1, 0, 1]
	s_nop 0
	v_cvt_pk_bf16_f32 v66, v70, v71
	v_cvt_pk_bf16_f32 v67, v72, v73
	global_store_dwordx2 v[80:81], v[66:67], off offset:32
	v_mul_f32_e32 v71, v71, v71
	v_mul_f32_e32 v73, v73, v73
	v_fmac_f32_e32 v71, v70, v70
	v_fmac_f32_e32 v73, v72, v72
	v_add_f32_e32 v70, v71, v73
	v_add_f32_e32 v70, v74, v70
	s_waitcnt vmcnt(3)
	s_nop 1
	v_pk_fma_f32 v[68:69], v[64:65], 0.5, v[106:107] op_sel_hi:[1, 0, 1]
	v_pk_fma_f32 v[66:67], v[62:63], 0.5, v[104:105] op_sel_hi:[1, 0, 1]
	s_nop 0
	v_cvt_pk_bf16_f32 v62, v66, v67
	v_cvt_pk_bf16_f32 v63, v68, v69
	global_store_dwordx2 v[80:81], v[62:63], off offset:256
	v_mul_f32_e32 v67, v67, v67
	v_mul_f32_e32 v69, v69, v69
	v_fmac_f32_e32 v67, v66, v66
	v_fmac_f32_e32 v69, v68, v68
	v_add_f32_e32 v66, v67, v69
	v_add_f32_e32 v66, v70, v66
	s_waitcnt vmcnt(3)
	s_nop 1
	v_pk_fma_f32 v[60:61], v[60:61], 0.5, v[110:111] op_sel_hi:[1, 0, 1]
	v_pk_fma_f32 v[58:59], v[58:59], 0.5, v[108:109] op_sel_hi:[1, 0, 1]
	v_mul_f32_e32 v63, v61, v61
	v_mul_f32_e32 v62, v59, v59
	v_fmac_f32_e32 v62, v58, v58
	v_fmac_f32_e32 v63, v60, v60
	v_add_f32_e32 v62, v62, v63
	v_add_f32_e32 v62, v66, v62
	ds_bpermute_b32 v0, v0, v62
	v_xor_b32_e32 v63, 32, v236
	v_cmp_lt_i32_e32 vcc, v63, v7
	v_cvt_pk_bf16_f32 v58, v58, v59
	v_cvt_pk_bf16_f32 v59, v60, v61
	s_waitcnt lgkmcnt(0)
	v_add_f32_e32 v0, v62, v0
	global_store_dwordx2 v[80:81], v[58:59], off offset:288
	v_cndmask_b32_e32 v7, v236, v63, vcc
	v_lshlrev_b32_e32 v7, 2, v7
	ds_bpermute_b32 v7, v7, v0
	s_and_b64 exec, exec, s[8:9]
	s_cbranch_execz .LBB0_462
	v_lshl_add_u64 v[58:59], v[8:9], 2, s[30:31]
	s_waitcnt lgkmcnt(0)
	v_add_f32_e32 v0, v0, v7
	global_atomic_add_f32 v[58:59], v0, off

; __device__ __forceinline__ unsigned cvt_pk_bf16(float lo, float hi) { unsigned r; asm volatile("v_cvt_pk_bf16_f32 %0, %1, %2" : "=v"(r) : "v"(lo), "v"(hi)); return r; }
;     __device__ __forceinline__ void operator()(const f32x4 (&acc)[2][2][4][2], const pg8::Unit& u, int wr, int wc, int fr, int fq) const {
;     ...
;             for (int m = 0; m < 4; ++m) { const int row = row0 + ai * 128 + m * 16;
;                 if (row < MV) {
;                     const float* rp = (row < MPR) ? res_p + (size_t)row * DM : res_s + (size_t)(row - MPR) * DM;
;                     float s = 0.f;
; #pragma unroll
;                     for (int bj = 0; bj < 2; ++bj)
; #pragma unroll
;                         for (int n = 0; n < 2; ++n) { const int col = col0 + bj * 128 + n * 16; f32x4 r;
;                             if (RESB) { const u32x2 rw = *(const u32x2*)(resb + (size_t)row * DM + col); r = (f32x4){bf2f(rw.x & 0xffff), bf2f(rw.x >> 16), bf2f(rw.y & 0xffff), bf2f(rw.y >> 16)}; }
;                             else r = *(const f32x4*)(rp + col);
;                             const f32x4 v = r + acc[ai][bj][m][n] * scale;
;                             if (OUTF) *(f32x4*)(out + (size_t)row * DM + col) = v;
;                             else { u32x2 w; w.x = cvt_pk_bf16(v[0], v[1]); w.y = cvt_pk_bf16(v[2], v[3]); *(u32x2*)(outb + (size_t)row * DM + col) = w;
;                                 s += (v[0] * v[0] + v[1] * v[1]) + (v[2] * v[2] + v[3] * v[3]); } }
;                     if (!OUTF) { s += __shfl_xor(s, 16); s += __shfl_xor(s, 32); if (fq == 0) atomicAdd(ss + row, s); }
.LBB0_467:
	s_or_b64 exec, exec, s[6:7]
	s_waitcnt lgkmcnt(0)
	v_ashrrev_i32_e32 v7, 31, v6
	s_waitcnt vmcnt(48)
	v_lshl_add_u64 v[64:65], v[6:7], 2, v[60:61]
	global_load_dwordx4 v[60:63], v[64:65], off
	global_load_dwordx4 v[100:103], v[64:65], off offset:64
	global_load_dwordx4 v[104:107], v[64:65], off offset:512
	global_load_dwordx4 v[108:111], v[64:65], off offset:576
	v_lshlrev_b64 v[66:67], 11, v[58:59]
	v_lshl_add_u64 v[66:67], s[28:29], 0, v[66:67]
	v_lshl_add_u64 v[66:67], v[6:7], 1, v[66:67]
	v_and_b32_e32 v7, 64, v236
	v_xor_b32_e32 v0, 16, v236
	v_add_u32_e32 v7, 64, v7
	v_cmp_lt_i32_e32 vcc, v0, v7
	s_waitcnt vmcnt(3)
	s_nop 1
	v_pk_fma_f32 v[62:63], v[56:57], 0.5, v[62:63] op_sel_hi:[1,0,1]
	v_pk_fma_f32 v[60:61], v[54:55], 0.5, v[60:61] op_sel_hi:[1,0,1]
	v_cndmask_b32_e32 v0, v236, v0, vcc
	v_cvt_pk_bf16_f32 v54, v60, v61
	v_cvt_pk_bf16_f32 v55, v62, v63
	global_store_dwordx2 v[66:67], v[54:55], off
	v_mul_f32_e32 v9, v61, v61
	v_mul_f32_e32 v61, v63, v63
	v_fmac_f32_e32 v9, v60, v60
	v_fmac_f32_e32 v61, v62, v62
	v_add_f32_e32 v9, v9, v61
	v_lshlrev_b32_e32 v0, 2, v0
	s_waitcnt vmcnt(3)
	s_nop 1
	v_pk_fma_f32 v[56:57], v[52:53], 0.5, v[102:103] op_sel_hi:[1, 0, 1]
	v_pk_fma_f32 v[54:55], v[50:51], 0.5, v[100:101] op_sel_hi:[1, 0, 1]
	s_nop 0
	v_cvt_pk_bf16_f32 v50, v54, v55
	v_cvt_pk_bf16_f32 v51, v56, v57
	global_store_dwordx2 v[66:67], v[50:51], off offset:32
	v_mul_f32_e32 v55, v55, v55
	v_mul_f32_e32 v57, v57, v57
	v_fmac_f32_e32 v55, v54, v54
	v_fmac_f32_e32 v57, v56, v56
	v_add_f32_e32 v54, v55, v57
	v_add_f32_e32 v9, v9, v54
	s_waitcnt vmcnt(3)
	s_nop 1
	v_pk_fma_f32 v[52:53], v[48:49], 0.5, v[106:107] op_sel_hi:[1, 0, 1]
	v_pk_fma_f32 v[50:51], v[46:47], 0.5, v[104:105] op_sel_hi:[1, 0, 1]
	s_nop 0
	v_cvt_pk_bf16_f32 v46, v50, v51
	v_cvt_pk_bf16_f32 v47, v52, v53
	global_store_dwordx2 v[66:67], v[46:47], off offset:256
	v_mul_f32_e32 v51, v51, v51
	v_mul_f32_e32 v53, v53, v53
	v_fmac_f32_e32 v51, v50, v50
	v_fmac_f32_e32 v53, v52, v52
	v_add_f32_e32 v50, v51, v53
	v_add_f32_e32 v9, v9, v50
	s_waitcnt vmcnt(3)
	s_nop 1
	v_pk_fma_f32 v[44:45], v[44:45], 0.5, v[110:111] op_sel_hi:[1, 0, 1]
	v_pk_fma_f32 v[42:43], v[42:43], 0.5, v[108:109] op_sel_hi:[1, 0, 1]
	v_mul_f32_e32 v47, v45, v45
	v_mul_f32_e32 v46, v43, v43
	v_fmac_f32_e32 v46, v42, v42
	v_fmac_f32_e32 v47, v44, v44
	v_add_f32_e32 v46, v46, v47
	v_add_f32_e32 v9, v9, v46
	ds_bpermute_b32 v0, v0, v9
	v_xor_b32_e32 v46, 32, v236
	v_cmp_lt_i32_e32 vcc, v46, v7
	v_cvt_pk_bf16_f32 v42, v42, v43
	v_cvt_pk_bf16_f32 v43, v44, v45
	s_waitcnt lgkmcnt(0)
	v_add_f32_e32 v0, v9, v0
	global_store_dwordx2 v[66:67], v[42:43], off offset:288
	v_cndmask_b32_e32 v7, v236, v46, vcc
	v_lshlrev_b32_e32 v7, 2, v7
	ds_bpermute_b32 v7, v7, v0
	s_and_b64 exec, exec, s[8:9]
	s_cbranch_execz .LBB0_469
	v_lshl_add_u64 v[42:43], v[58:59], 2, s[30:31]
	s_waitcnt lgkmcnt(0)
	v_add_f32_e32 v0, v0, v7
	global_atomic_add_f32 v[42:43], v0, off

; __device__ __forceinline__ unsigned cvt_pk_bf16(float lo, float hi) { unsigned r; asm volatile("v_cvt_pk_bf16_f32 %0, %1, %2" : "=v"(r) : "v"(lo), "v"(hi)); return r; }
;     __device__ __forceinline__ void operator()(const f32x4 (&acc)[2][2][4][2], const pg8::Unit& u, int wr, int wc, int fr, int fq) const {
;     ...
;             for (int m = 0; m < 4; ++m) { const int row = row0 + ai * 128 + m * 16;
;                 if (row < MV) {
;                     const float* rp = (row < MPR) ? res_p + (size_t)row * DM : res_s + (size_t)(row - MPR) * DM;
;                     float s = 0.f;
; #pragma unroll
;                     for (int bj = 0; bj < 2; ++bj)
; #pragma unroll
;                         for (int n = 0; n < 2; ++n) { const int col = col0 + bj * 128 + n * 16; f32x4 r;
;                             if (RESB) { const u32x2 rw = *(const u32x2*)(resb + (size_t)row * DM + col); r = (f32x4){bf2f(rw.x & 0xffff), bf2f(rw.x >> 16), bf2f(rw.y & 0xffff), bf2f(rw.y >> 16)}; }
;                             else r = *(const f32x4*)(rp + col);
;                             const f32x4 v = r + acc[ai][bj][m][n] * scale;
;                             if (OUTF) *(f32x4*)(out + (size_t)row * DM + col) = v;
;                             else { u32x2 w; w.x = cvt_pk_bf16(v[0], v[1]); w.y = cvt_pk_bf16(v[2], v[3]); *(u32x2*)(outb + (size_t)row * DM + col) = w;
;                                 s += (v[0] * v[0] + v[1] * v[1]) + (v[2] * v[2] + v[3] * v[3]); } }
;                     if (!OUTF) { s += __shfl_xor(s, 16); s += __shfl_xor(s, 32); if (fq == 0) atomicAdd(ss + row, s); }
.LBB0_474:
	s_or_b64 exec, exec, s[6:7]
	s_waitcnt lgkmcnt(0)
	v_ashrrev_i32_e32 v7, 31, v6
	s_waitcnt vmcnt(32)
	v_lshl_add_u64 v[48:49], v[6:7], 2, v[44:45]
	global_load_dwordx4 v[44:47], v[48:49], off
	global_load_dwordx4 v[100:103], v[48:49], off offset:64
	global_load_dwordx4 v[104:107], v[48:49], off offset:512
	global_load_dwordx4 v[108:111], v[48:49], off offset:576
	v_lshlrev_b64 v[50:51], 11, v[42:43]
	v_lshl_add_u64 v[50:51], s[28:29], 0, v[50:51]
	v_lshl_add_u64 v[50:51], v[6:7], 1, v[50:51]
	v_and_b32_e32 v7, 64, v236
	v_xor_b32_e32 v0, 16, v236
	v_add_u32_e32 v7, 64, v7
	v_cmp_lt_i32_e32 vcc, v0, v7
	s_waitcnt vmcnt(3)
	s_nop 1
	v_pk_fma_f32 v[46:47], v[40:41], 0.5, v[46:47] op_sel_hi:[1,0,1]
	v_pk_fma_f32 v[44:45], v[38:39], 0.5, v[44:45] op_sel_hi:[1,0,1]
	v_cndmask_b32_e32 v0, v236, v0, vcc
	v_cvt_pk_bf16_f32 v38, v44, v45
	v_cvt_pk_bf16_f32 v39, v46, v47
	global_store_dwordx2 v[50:51], v[38:39], off
	v_mul_f32_e32 v9, v45, v45
	v_mul_f32_e32 v45, v47, v47
	v_fmac_f32_e32 v9, v44, v44
	v_fmac_f32_e32 v45, v46, v46
	v_add_f32_e32 v9, v9, v45
	v_lshlrev_b32_e32 v0, 2, v0
	s_waitcnt vmcnt(3)
	s_nop 1
	v_pk_fma_f32 v[40:41], v[36:37], 0.5, v[102:103] op_sel_hi:[1, 0, 1]
	v_pk_fma_f32 v[38:39], v[34:35], 0.5, v[100:101] op_sel_hi:[1, 0, 1]
	s_nop 0
	v_cvt_pk_bf16_f32 v34, v38, v39
	v_cvt_pk_bf16_f32 v35, v40, v41
	global_store_dwordx2 v[50:51], v[34:35], off offset:32
	v_mul_f32_e32 v39, v39, v39
	v_mul_f32_e32 v41, v41, v41
	v_fmac_f32_e32 v39, v38, v38
	v_fmac_f32_e32 v41, v40, v40
	v_add_f32_e32 v38, v39, v41
	v_add_f32_e32 v9, v9, v38
	s_waitcnt vmcnt(3)
	s_nop 1
	v_pk_fma_f32 v[36:37], v[32:33], 0.5, v[106:107] op_sel_hi:[1, 0, 1]
	v_pk_fma_f32 v[34:35], v[30:31], 0.5, v[104:105] op_sel_hi:[1, 0, 1]
	s_nop 0
	v_cvt_pk_bf16_f32 v30, v34, v35
	v_cvt_pk_bf16_f32 v31, v36, v37
	global_store_dwordx2 v[50:51], v[30:31], off offset:256
	v_mul_f32_e32 v35, v35, v35
	v_mul_f32_e32 v37, v37, v37
	v_fmac_f32_e32 v35, v34, v34
	v_fmac_f32_e32 v37, v36, v36
	v_add_f32_e32 v34, v35, v37
	v_add_f32_e32 v9, v9, v34
	s_waitcnt vmcnt(3)
	s_nop 1
	v_pk_fma_f32 v[28:29], v[28:29], 0.5, v[110:111] op_sel_hi:[1, 0, 1]
	v_pk_fma_f32 v[26:27], v[26:27], 0.5, v[108:109] op_sel_hi:[1, 0, 1]
	v_mul_f32_e32 v31, v29, v29
	v_mul_f32_e32 v30, v27, v27
	v_fmac_f32_e32 v30, v26, v26
	v_fmac_f32_e32 v31, v28, v28
	v_add_f32_e32 v30, v30, v31
	v_add_f32_e32 v9, v9, v30
	ds_bpermute_b32 v0, v0, v9
	v_xor_b32_e32 v30, 32, v236
	v_cmp_lt_i32_e32 vcc, v30, v7
	v_cvt_pk_bf16_f32 v26, v26, v27
	v_cvt_pk_bf16_f32 v27, v28, v29
	s_waitcnt lgkmcnt(0)
	v_add_f32_e32 v0, v9, v0
	global_store_dwordx2 v[50:51], v[26:27], off offset:288
	v_cndmask_b32_e32 v7, v236, v30, vcc
	v_lshlrev_b32_e32 v7, 2, v7
	ds_bpermute_b32 v7, v7, v0
	s_and_b64 exec, exec, s[8:9]
	s_cbranch_execz .LBB0_476
	v_lshl_add_u64 v[26:27], v[42:43], 2, s[30:31]
	s_waitcnt lgkmcnt(0)
	v_add_f32_e32 v0, v0, v7
	global_atomic_add_f32 v[26:27], v0, off

; __device__ __forceinline__ unsigned cvt_pk_bf16(float lo, float hi) { unsigned r; asm volatile("v_cvt_pk_bf16_f32 %0, %1, %2" : "=v"(r) : "v"(lo), "v"(hi)); return r; }
;     __device__ __forceinline__ void operator()(const f32x4 (&acc)[2][2][4][2], const pg8::Unit& u, int wr, int wc, int fr, int fq) const {
;     ...
;             for (int m = 0; m < 4; ++m) { const int row = row0 + ai * 128 + m * 16;
;                 if (row < MV) {
;                     const float* rp = (row < MPR) ? res_p + (size_t)row * DM : res_s + (size_t)(row - MPR) * DM;
;                     float s = 0.f;
; #pragma unroll
;                     for (int bj = 0; bj < 2; ++bj)
; #pragma unroll
;                         for (int n = 0; n < 2; ++n) { const int col = col0 + bj * 128 + n * 16; f32x4 r;
;                             if (RESB) { const u32x2 rw = *(const u32x2*)(resb + (size_t)row * DM + col); r = (f32x4){bf2f(rw.x & 0xffff), bf2f(rw.x >> 16), bf2f(rw.y & 0xffff), bf2f(rw.y >> 16)}; }
;                             else r = *(const f32x4*)(rp + col);
;                             const f32x4 v = r + acc[ai][bj][m][n] * scale;
;                             if (OUTF) *(f32x4*)(out + (size_t)row * DM + col) = v;
;                             else { u32x2 w; w.x = cvt_pk_bf16(v[0], v[1]); w.y = cvt_pk_bf16(v[2], v[3]); *(u32x2*)(outb + (size_t)row * DM + col) = w;
;                                 s += (v[0] * v[0] + v[1] * v[1]) + (v[2] * v[2] + v[3] * v[3]); } }
;                     if (!OUTF) { s += __shfl_xor(s, 16); s += __shfl_xor(s, 32); if (fq == 0) atomicAdd(ss + row, s); }
.LBB0_481:
	s_or_b64 exec, exec, s[6:7]
	s_waitcnt lgkmcnt(0)
	v_ashrrev_i32_e32 v7, 31, v6
	s_waitcnt vmcnt(16)
	v_lshl_add_u64 v[32:33], v[6:7], 2, v[28:29]
	global_load_dwordx4 v[28:31], v[32:33], off
	global_load_dwordx4 v[100:103], v[32:33], off offset:64
	global_load_dwordx4 v[104:107], v[32:33], off offset:512
	global_load_dwordx4 v[108:111], v[32:33], off offset:576
	v_lshlrev_b64 v[34:35], 11, v[26:27]
	v_lshl_add_u64 v[34:35], s[28:29], 0, v[34:35]
	v_lshl_add_u64 v[34:35], v[6:7], 1, v[34:35]
	v_and_b32_e32 v7, 64, v236
	v_xor_b32_e32 v0, 16, v236
	v_add_u32_e32 v7, 64, v7
	v_cmp_lt_i32_e32 vcc, v0, v7
	s_waitcnt vmcnt(3)
	s_nop 1
	v_pk_fma_f32 v[30:31], v[24:25], 0.5, v[30:31] op_sel_hi:[1,0,1]
	v_pk_fma_f32 v[28:29], v[22:23], 0.5, v[28:29] op_sel_hi:[1,0,1]
	v_cndmask_b32_e32 v0, v236, v0, vcc
	v_cvt_pk_bf16_f32 v22, v28, v29
	v_cvt_pk_bf16_f32 v23, v30, v31
	global_store_dwordx2 v[34:35], v[22:23], off
	v_mul_f32_e32 v9, v29, v29
	v_mul_f32_e32 v29, v31, v31
	v_fmac_f32_e32 v9, v28, v28
	v_fmac_f32_e32 v29, v30, v30
	v_add_f32_e32 v9, v9, v29
	v_lshlrev_b32_e32 v0, 2, v0
	s_waitcnt vmcnt(3)
	s_nop 1
	v_pk_fma_f32 v[24:25], v[20:21], 0.5, v[102:103] op_sel_hi:[1, 0, 1]
	v_pk_fma_f32 v[22:23], v[18:19], 0.5, v[100:101] op_sel_hi:[1, 0, 1]
	s_nop 0
	v_cvt_pk_bf16_f32 v18, v22, v23
	v_cvt_pk_bf16_f32 v19, v24, v25
	global_store_dwordx2 v[34:35], v[18:19], off offset:32
	v_mul_f32_e32 v23, v23, v23
	v_mul_f32_e32 v25, v25, v25
	v_fmac_f32_e32 v23, v22, v22
	v_fmac_f32_e32 v25, v24, v24
	v_add_f32_e32 v22, v23, v25
	v_add_f32_e32 v9, v9, v22
	s_waitcnt vmcnt(3)
	s_nop 1
	v_pk_fma_f32 v[20:21], v[16:17], 0.5, v[106:107] op_sel_hi:[1, 0, 1]
	v_pk_fma_f32 v[18:19], v[14:15], 0.5, v[104:105] op_sel_hi:[1, 0, 1]
	s_nop 0
	v_cvt_pk_bf16_f32 v14, v18, v19
	v_cvt_pk_bf16_f32 v15, v20, v21
	global_store_dwordx2 v[34:35], v[14:15], off offset:256
	v_mul_f32_e32 v19, v19, v19
	v_mul_f32_e32 v21, v21, v21
	v_fmac_f32_e32 v19, v18, v18
	v_fmac_f32_e32 v21, v20, v20
	v_add_f32_e32 v18, v19, v21
	v_add_f32_e32 v9, v9, v18
	s_waitcnt vmcnt(3)
	s_nop 1
	v_pk_fma_f32 v[12:13], v[12:13], 0.5, v[110:111] op_sel_hi:[1, 0, 1]
	v_pk_fma_f32 v[10:11], v[10:11], 0.5, v[108:109] op_sel_hi:[1, 0, 1]
	v_mul_f32_e32 v15, v13, v13
	v_mul_f32_e32 v14, v11, v11
	v_fmac_f32_e32 v14, v10, v10
	v_fmac_f32_e32 v15, v12, v12
	v_add_f32_e32 v14, v14, v15
	v_add_f32_e32 v9, v9, v14
	ds_bpermute_b32 v0, v0, v9
	v_xor_b32_e32 v14, 32, v236
	v_cmp_lt_i32_e32 vcc, v14, v7
	v_cvt_pk_bf16_f32 v10, v10, v11
	v_cvt_pk_bf16_f32 v11, v12, v13
	s_waitcnt lgkmcnt(0)
	v_add_f32_e32 v0, v9, v0
	global_store_dwordx2 v[34:35], v[10:11], off offset:288
	v_cndmask_b32_e32 v7, v236, v14, vcc
	v_lshlrev_b32_e32 v7, 2, v7
	ds_bpermute_b32 v7, v7, v0
	s_and_b64 exec, exec, s[8:9]
	s_cbranch_execz .LBB0_483
	v_lshl_add_u64 v[10:11], v[26:27], 2, s[30:31]
	s_waitcnt lgkmcnt(0)
	v_add_f32_e32 v0, v0, v7
	global_atomic_add_f32 v[10:11], v0, off

; #define TID_NOW(wave_sg) tid_now_(wave_sg)
; template <int L, int R> __device__ __forceinline__ void copy_seg(const float* __restrict__ src, float* __restrict__ dst, unsigned lo, unsigned hi, unsigned t0, unsigned nthr) {
;     constexpr unsigned PER = (unsigned)(L - 1) * R / 4, LR4 = (unsigned)L * R / 4, R4 = R / 4;
;     const f32x4* s4 = (const f32x4*)src; f32x4* d4 = (f32x4*)dst;
;     unsigned i = lo + t0;
;     for (; i + 3 * nthr < hi; i += 4 * nthr) {
; __device__ __forceinline__ void idle_copy(KParams P, int nwg, unsigned lo, unsigned hi, const int wave_sg) {
;     const int G = gridDim.x, busy = nwg % G; const int tid = TID_NOW(wave_sg);
;     if (busy == 0 || (int)blockIdx.x < busy) { if (busy == 0) copy_slice(P, lo, hi, blockIdx.x * 512 + tid, G * 512); return; }
;     copy_slice(P, lo, hi, (blockIdx.x - busy) * 512 + tid, (G - busy) * 512);
.LBB0_730:
	v_readlane_b32 s0, v255, 18
	v_readlane_b32 s1, v255, 19
	s_cmp_gt_i32 s2, 21
	s_cbranch_scc0 .Lmvb1_done
	s_and_b64 vcc, exec, s[0:1]
	s_cbranch_vccnz .Lmvb1_done
	v_mbcnt_lo_u32_b32 v0, -1, 0
	v_mbcnt_hi_u32_b32 v0, -1, v0
	v_lshl_or_b32 v0, s96, 6, v0
	s_lshl_b32 s3, s2, 9
	s_addk_i32 s3, 0xd400
	v_add_u32_e32 v2, s3, v0
	v_add_u32_e32 v3, 0x57c00, v2
	v_readlane_b32 s6, v255, 2
	v_readlane_b32 s7, v255, 3
	s_nop 0
	s_load_dwordx2 s[8:9], s[6:7], 0xc0
	s_waitcnt lgkmcnt(0)
	s_load_dwordx2 s[4:5], s[6:7], 0x18
	s_add_u32 s10, s8, 0xe680000
	s_mov_b32 s3, 0x1fc000
	s_addc_u32 s11, s9, 0
	v_cmp_gt_u32_e32 vcc, s3, v3
	s_and_saveexec_b64 s[12:13], vcc
	s_cbranch_execz .Lmvb1_280
	s_mov_b64 s[14:15], 0
	s_mov_b32 s3, 0x2040811
	s_movk_i32 s16, 0xc080
	v_mov_b32_e32 v1, 0
	s_mov_b32 s17, 0x1fbfff

; #define TID_NOW(wave_sg) tid_now_(wave_sg)
; __device__ __forceinline__ unsigned xb_ld(unsigned* p)              { return __hip_atomic_load(p, __ATOMIC_RELAXED, __HIP_MEMORY_SCOPE_AGENT); }
; __device__ __forceinline__ void xcd_barrier_complete(unsigned* bar, unsigned x, unsigned& nloc, unsigned& nx) {
;     const unsigned G = gridDim.x * gridDim.y * gridDim.z;
;     unsigned sum, cnt, mine, sp = 0u;
;     for (;;) {
;         sum = 0u; cnt = 0u; mine = 0u;
; #pragma unroll
;         for (unsigned j = 0; j < 16; ++j) { const unsigned c = xb_ld(&bar[XB_XCNT(j)]); sum += c; cnt += (c > 0u) ? 1u : 0u; mine = (j == x) ? c : mine; }
; __device__ __forceinline__ void xcd_barrier(const XcdBarrier& b, int wave_sg) {
;     asm volatile("s_waitcnt vmcnt(0)" ::: "memory");
;     __syncthreads();
;     if (TID_NOW(wave_sg) == 0) {
;         unsigned* bar = b.bar;
;         __builtin_amdgcn_s_waitcnt(0);
;         unsigned nloc = b.st[0], nx = b.st[1];
;         if (nloc == 0u) { xcd_barrier_complete(bar, b.x, nloc, nx); b.st[0] = nloc; b.st[1] = nx; }
.Lmvb1_283:
	s_or_b64 exec, exec, s[12:13]
.Lmvb1_done:
	s_waitcnt vmcnt(0)
	s_waitcnt vmcnt(0)
	s_barrier
	v_mbcnt_lo_u32_b32 v0, -1, 0
	v_mbcnt_hi_u32_b32 v0, -1, v0
	v_lshl_or_b32 v0, s96, 6, v0
	s_nop 0
	v_cmp_eq_u32_e32 vcc, 0, v0
	s_and_saveexec_b64 s[0:1], vcc
	s_cbranch_execz .LBB0_782
	s_add_i32 s3, 0, 0x25ff0
	v_mov_b32_e32 v0, s3
	s_waitcnt vmcnt(0) expcnt(0) lgkmcnt(0)
	ds_read_b32 v2, v0
	s_add_i32 s3, 0, 0x25ff4
	v_mov_b32_e32 v0, s3
	ds_read_b32 v0, v0
	s_waitcnt lgkmcnt(1)
	v_cmp_ne_u32_e32 vcc, 0, v2
	s_cbranch_vccnz .LBB0_746
	v_readlane_b32 s6, v255, 2
	v_readlane_b32 s7, v255, 3
	s_load_dwordx2 s[4:5], s[6:7], 0xd0
	s_load_dword s3, s[6:7], 0xd8
	s_load_dwordx2 s[42:43], s[6:7], 0xc8
	s_mov_b32 s21, 1
	v_mov_b32_e32 v16, 0
	s_waitcnt lgkmcnt(0)
	s_mul_i32 s3, s5, s3
	s_mul_i32 s3, s3, s4
	s_add_u32 s4, s42, 0x49800200
	s_addc_u32 s5, s43, 0
	s_add_u32 s6, s42, 0x49800400
	s_addc_u32 s7, s43, 0
	s_add_u32 s8, s42, 0x49800500
	s_addc_u32 s9, s43, 0
	s_add_u32 s10, s42, 0x49800600
	s_addc_u32 s11, s43, 0
	s_add_u32 s12, s42, 0x49800700
	s_addc_u32 s13, s43, 0
	s_add_u32 s14, s42, 0x49800800
	s_addc_u32 s15, s43, 0
	s_add_u32 s16, s42, 0x49800900
	s_addc_u32 s17, s43, 0
	s_add_u32 s18, s42, 0x49800a00
	s_addc_u32 s19, s43, 0
	s_add_u32 s24, s42, 0x49800b00
	s_addc_u32 s25, s43, 0
	s_add_u32 s26, s42, 0x49800c00
	s_addc_u32 s27, s43, 0
	s_add_u32 s28, s42, 0x49800d00
	s_addc_u32 s29, s43, 0
	s_add_u32 s30, s42, 0x49800e00
	s_addc_u32 s31, s43, 0
	s_add_u32 s34, s42, 0x49800f00
	s_addc_u32 s35, s43, 0
	s_add_u32 s36, s42, 0x49801000
	s_addc_u32 s37, s43, 0
	s_add_u32 s38, s42, 0x49801100
	s_addc_u32 s39, s43, 0
	s_add_u32 s40, s42, 0x49801200
	s_addc_u32 s41, s43, 0
	s_add_u32 s42, s42, 0x49801300
	s_addc_u32 s43, s43, 0
	s_branch .LBB0_734

; #define PG8_LAS __attribute__((address_space(3)))
; #define PG8_BAR __builtin_amdgcn_s_barrier()
; template <class Epi, class Sched, bool ALIGN_EPI = false, bool SP2 = false, class Bg = BgNone>
; __device__ __forceinline__ void gemm_phase(PG8_LAS unsigned char* lds, const Gemm g, const Sched& S, const Epi& E, const int wave_sg, const Bg& bg = Bg()) {
;     ...
;             PG8_LAS unsigned* flag = (PG8_LAS unsigned*)(lds + STAGE_BYTES);
;             PG8_BAR;
;             if (tid == 0) { const unsigned old = __hip_atomic_fetch_add(S.cnt + cur.pn, 1u, __ATOMIC_ACQ_REL, __HIP_MEMORY_SCOPE_AGENT); *flag = (old == (unsigned)cur.split - 1u) ? 1u : 0u; }
;             asm volatile("s_waitcnt lgkmcnt(0)" ::: "memory"); PG8_BAR; asm volatile("" ::: "memory");
;             const bool lastone = *flag != 0u;
;             asm volatile("s_waitcnt lgkmcnt(0)" ::: "memory"); PG8_BAR;
;             if (lastone) { __threadfence();
; #pragma unroll
;                 for (int m = 0; m < 4; ++m)
; #pragma unroll
;                     for (int bj = 0; bj < 2; ++bj)
; #pragma unroll
;                         for (int n = 0; n < 2; ++n) {
; #pragma unroll
;                             for (int c = 0; c < 4; ++c) acc[0][bj][m][n][c] = __hip_atomic_load(ab + (((m * 2 + bj) * 2 + n) * 4 + c) * 512, __ATOMIC_RELAXED, __HIP_MEMORY_SCOPE_AGENT);
.LBB0_1320:
	s_or_b64 exec, exec, s[52:53]
	s_mov_b64 s[52:53], 0x1000
	v_lshl_add_u64 v[6:7], v[34:35], 0, s[52:53]
	s_mov_b64 s[52:53], 0x1800
	v_lshl_add_u64 v[8:9], v[34:35], 0, s[52:53]
	s_mov_b64 s[52:53], 0x2000
	v_lshl_add_u64 v[10:11], v[34:35], 0, s[52:53]
	s_mov_b64 s[52:53], 0x2800
	v_lshl_add_u64 v[12:13], v[34:35], 0, s[52:53]
	s_mov_b64 s[52:53], 0x3000
	v_lshl_add_u64 v[14:15], v[34:35], 0, s[52:53]
	s_mov_b64 s[52:53], 0x3800
	v_lshl_add_u64 v[16:17], v[34:35], 0, s[52:53]
	s_mov_b64 s[52:53], 0x4000
	v_lshl_add_u64 v[18:19], v[34:35], 0, s[52:53]
	s_mov_b64 s[52:53], 0x4800
	v_lshl_add_u64 v[20:21], v[34:35], 0, s[52:53]
	s_mov_b64 s[52:53], 0x5000
	v_lshl_add_u64 v[22:23], v[34:35], 0, s[52:53]
	s_mov_b64 s[52:53], 0x5800
	v_lshl_add_u64 v[24:25], v[34:35], 0, s[52:53]
	s_mov_b64 s[52:53], 0x6000
	v_lshl_add_u64 v[26:27], v[34:35], 0, s[52:53]
	s_mov_b64 s[52:53], 0x6800
	v_lshl_add_u64 v[28:29], v[34:35], 0, s[52:53]
	s_mov_b64 s[52:53], 0x7000
	v_lshl_add_u64 v[30:31], v[34:35], 0, s[52:53]
	s_mov_b64 s[52:53], 0x7800
	v_lshl_add_u64 v[32:33], v[34:35], 0, s[52:53]
	s_mov_b64 s[52:53], 0x8000
	v_lshl_add_u64 v[36:37], v[34:35], 0, s[52:53]
	s_mov_b64 s[52:53], 0x8800
	v_lshl_add_u64 v[38:39], v[34:35], 0, s[52:53]
	s_mov_b64 s[52:53], 0x9000
	v_lshl_add_u64 v[40:41], v[34:35], 0, s[52:53]
	s_mov_b64 s[52:53], 0x9800
	v_lshl_add_u64 v[42:43], v[34:35], 0, s[52:53]
	s_mov_b64 s[52:53], 0xa000
	v_lshl_add_u64 v[44:45], v[34:35], 0, s[52:53]
	s_mov_b64 s[52:53], 0xa800
	v_lshl_add_u64 v[46:47], v[34:35], 0, s[52:53]
	s_mov_b64 s[52:53], 0xb000
	v_lshl_add_u64 v[48:49], v[34:35], 0, s[52:53]
	s_mov_b64 s[52:53], 0xb800
	v_lshl_add_u64 v[74:75], v[34:35], 0, s[52:53]
	s_mov_b64 s[52:53], 0xc000
	v_lshl_add_u64 v[76:77], v[34:35], 0, s[52:53]
	s_mov_b64 s[52:53], 0xc800
	v_lshl_add_u64 v[78:79], v[34:35], 0, s[52:53]
	s_mov_b64 s[52:53], 0xd000
	v_lshl_add_u64 v[80:81], v[34:35], 0, s[52:53]
	s_mov_b64 s[52:53], 0xd800
	v_lshl_add_u64 v[82:83], v[34:35], 0, s[52:53]
	s_mov_b64 s[52:53], 0xe000
	v_lshl_add_u64 v[84:85], v[34:35], 0, s[52:53]
	s_mov_b64 s[52:53], 0xe800
	v_lshl_add_u64 v[86:87], v[34:35], 0, s[52:53]
	s_mov_b64 s[52:53], 0xf000
	v_lshl_add_u64 v[88:89], v[34:35], 0, s[52:53]
	s_mov_b64 s[52:53], 0xf800
	v_lshl_add_u64 v[90:91], v[34:35], 0, s[52:53]
	s_mov_b64 s[52:53], 0x10000
	v_lshl_add_u64 v[92:93], v[34:35], 0, s[52:53]
	s_mov_b64 s[52:53], 0x10800
	v_lshl_add_u64 v[94:95], v[34:35], 0, s[52:53]
	s_mov_b64 s[52:53], 0x11000
	v_lshl_add_u64 v[96:97], v[34:35], 0, s[52:53]
	s_mov_b64 s[52:53], 0x11800
	v_lshl_add_u64 v[98:99], v[34:35], 0, s[52:53]
	s_mov_b64 s[52:53], 0x12000
	v_lshl_add_u64 v[100:101], v[34:35], 0, s[52:53]
	s_mov_b64 s[52:53], 0x12800
	v_lshl_add_u64 v[102:103], v[34:35], 0, s[52:53]
	s_mov_b64 s[52:53], 0x13000
	v_lshl_add_u64 v[104:105], v[34:35], 0, s[52:53]
	s_mov_b64 s[52:53], 0x13800
	v_lshl_add_u64 v[106:107], v[34:35], 0, s[52:53]
	s_mov_b64 s[52:53], 0x14000
	v_lshl_add_u64 v[108:109], v[34:35], 0, s[52:53]
	s_mov_b64 s[52:53], 0x14800
	v_lshl_add_u64 v[110:111], v[34:35], 0, s[52:53]
	s_mov_b64 s[52:53], 0x15000
	v_lshl_add_u64 v[112:113], v[34:35], 0, s[52:53]
	s_mov_b64 s[52:53], 0x15800
	v_lshl_add_u64 v[114:115], v[34:35], 0, s[52:53]
	s_mov_b64 s[52:53], 0x16000
	v_lshl_add_u64 v[116:117], v[34:35], 0, s[52:53]
	s_mov_b64 s[52:53], 0x16800
	v_lshl_add_u64 v[118:119], v[34:35], 0, s[52:53]
	s_mov_b64 s[52:53], 0x17000
	v_lshl_add_u64 v[120:121], v[34:35], 0, s[52:53]
	s_mov_b64 s[52:53], 0x17800
	s_waitcnt lgkmcnt(0)
	s_barrier
	v_mov_b32_e32 v0, s87
	v_lshl_add_u64 v[122:123], v[34:35], 0, s[52:53]
	s_mov_b64 s[52:53], 0x18000
	ds_read_b32 v0, v0
	v_lshl_add_u64 v[124:125], v[34:35], 0, s[52:53]
	s_mov_b64 s[52:53], 0x18800
	v_lshl_add_u64 v[126:127], v[34:35], 0, s[52:53]
	s_mov_b64 s[52:53], 0x19000
	v_lshl_add_u64 v[128:129], v[34:35], 0, s[52:53]
	s_mov_b64 s[52:53], 0x19800
	v_lshl_add_u64 v[130:131], v[34:35], 0, s[52:53]
	s_mov_b64 s[52:53], 0x1a000
	s_waitcnt lgkmcnt(0)
	v_lshl_add_u64 v[132:133], v[34:35], 0, s[52:53]
	s_mov_b64 s[52:53], 0x1a800
	s_waitcnt lgkmcnt(0)
	v_cmp_eq_u32_e32 vcc, 0, v0
	v_lshl_add_u64 v[134:135], v[34:35], 0, s[52:53]
	v_lshl_add_u64 v[136:137], v[34:35], 0, s[4:5]
	v_lshl_add_u64 v[138:139], v[34:35], 0, s[14:15]
	v_lshl_add_u64 v[140:141], v[34:35], 0, s[26:27]
	v_lshl_add_u64 v[142:143], v[34:35], 0, s[28:29]
	v_lshl_add_u64 v[144:145], v[34:35], 0, s[30:31]
	v_lshl_add_u64 v[146:147], v[34:35], 0, s[34:35]
	v_lshl_add_u64 v[148:149], v[34:35], 0, s[36:37]
	v_lshl_add_u64 v[150:151], v[34:35], 0, s[38:39]
	v_lshl_add_u64 v[152:153], v[34:35], 0, s[40:41]
	v_lshl_add_u64 v[154:155], v[34:35], 0, s[42:43]
	s_barrier
	s_cbranch_vccnz .LBB0_1343
; template <class Epi, class Sched, bool ALIGN_EPI = false, bool SP2 = false, class Bg = BgNone>
; __device__ __forceinline__ void gemm_phase(PG8_LAS unsigned char* lds, const Gemm g, const Sched& S, const Epi& E, const int wave_sg, const Bg& bg = Bg()) {
;     ...
;             if (lastone) { __threadfence();
; #pragma unroll
;                 for (int m = 0; m < 4; ++m)
; #pragma unroll
;                     for (int bj = 0; bj < 2; ++bj)
; #pragma unroll
;                         for (int n = 0; n < 2; ++n) {
; #pragma unroll
;                             for (int c = 0; c < 4; ++c) acc[0][bj][m][n][c] = __hip_atomic_load(ab + (((m * 2 + bj) * 2 + n) * 4 + c) * 512, __ATOMIC_RELAXED, __HIP_MEMORY_SCOPE_AGENT);
;     __device__ __forceinline__ void operator()(const f32x4 (&acc)[2][2][4][2], const pg8::Unit& u, int wr, int wc, int fr, int fq) const {
;     ...
;             for (int m = 0; m < 4; ++m) { const int row = row0 + ai * 128 + m * 16;
;                 if (row < MV) {
;                     const float* rp = (row < MPR) ? res_p + (size_t)row * DM : res_s + (size_t)(row - MPR) * DM;
;                     float s = 0.f;
; #pragma unroll
;                     for (int bj = 0; bj < 2; ++bj)
; #pragma unroll
;                         for (int n = 0; n < 2; ++n) { const int col = col0 + bj * 128 + n * 16; f32x4 r;
;                             if (RESB) { const u32x2 rw = *(const u32x2*)(resb + (size_t)row * DM + col); r = (f32x4){bf2f(rw.x & 0xffff), bf2f(rw.x >> 16), bf2f(rw.y & 0xffff), bf2f(rw.y >> 16)}; }
;                             else r = *(const f32x4*)(rp + col);
;                             const f32x4 v = r + acc[ai][bj][m][n] * scale;
;                             if (OUTF) *(f32x4*)(out + (size_t)row * DM + col) = v;
	buffer_wbl2 sc1
	buffer_inv sc1
	global_load_dword v70, v[34:35], off sc1
	global_load_dword v71, v[34:35], off offset:2048 sc1
	global_load_dword v72, v[6:7], off sc1
	global_load_dword v73, v[8:9], off sc1
	global_load_dword v68, v[10:11], off sc1
	global_load_dword v69, v[12:13], off sc1
	global_load_dword v66, v[14:15], off sc1
	global_load_dword v67, v[16:17], off sc1
	global_load_dword v64, v[18:19], off sc1
	global_load_dword v65, v[20:21], off sc1
	global_load_dword v62, v[22:23], off sc1
	global_load_dword v63, v[24:25], off sc1
	global_load_dword v60, v[26:27], off sc1
	global_load_dword v61, v[28:29], off sc1
	global_load_dword v58, v[30:31], off sc1
	global_load_dword v59, v[32:33], off sc1
	global_load_dword v54, v[36:37], off sc1
	global_load_dword v55, v[38:39], off sc1
	global_load_dword v56, v[40:41], off sc1
	global_load_dword v57, v[42:43], off sc1
	global_load_dword v52, v[44:45], off sc1
	global_load_dword v53, v[46:47], off sc1
	global_load_dword v50, v[48:49], off sc1
	global_load_dword v51, v[74:75], off sc1
	s_nop 0
	global_load_dword v48, v[76:77], off sc1
	global_load_dword v49, v[78:79], off sc1
	global_load_dword v46, v[80:81], off sc1
	global_load_dword v47, v[82:83], off sc1
	global_load_dword v44, v[84:85], off sc1
	global_load_dword v45, v[86:87], off sc1
	global_load_dword v42, v[88:89], off sc1
	global_load_dword v43, v[90:91], off sc1
	global_load_dword v38, v[92:93], off sc1
	global_load_dword v39, v[94:95], off sc1
	global_load_dword v40, v[96:97], off sc1
	global_load_dword v41, v[98:99], off sc1
	global_load_dword v36, v[100:101], off sc1
	global_load_dword v37, v[102:103], off sc1
	global_load_dword v34, v[104:105], off sc1
	global_load_dword v35, v[106:107], off sc1
	global_load_dword v32, v[108:109], off sc1
	global_load_dword v33, v[110:111], off sc1
	global_load_dword v30, v[112:113], off sc1
	global_load_dword v31, v[114:115], off sc1
	global_load_dword v28, v[116:117], off sc1
	global_load_dword v29, v[118:119], off sc1
	global_load_dword v26, v[120:121], off sc1
	global_load_dword v27, v[122:123], off sc1
	global_load_dword v22, v[124:125], off sc1
	global_load_dword v23, v[126:127], off sc1
	global_load_dword v24, v[128:129], off sc1
	global_load_dword v25, v[130:131], off sc1
	global_load_dword v20, v[132:133], off sc1
	global_load_dword v21, v[134:135], off sc1
	global_load_dword v18, v[136:137], off sc1
	global_load_dword v19, v[138:139], off sc1
	global_load_dword v16, v[140:141], off sc1
	global_load_dword v17, v[142:143], off sc1
	global_load_dword v14, v[144:145], off sc1
	global_load_dword v15, v[146:147], off sc1
	global_load_dword v12, v[148:149], off sc1
	global_load_dword v13, v[150:151], off sc1
	global_load_dword v10, v[152:153], off sc1
	global_load_dword v11, v[154:155], off sc1
	v_lshl_add_u32 v8, s93, 8, v230
	v_lshl_or_b32 v6, s48, 8, v232
	v_cmp_gt_i32_e32 vcc, s83, v8
	v_ashrrev_i32_e32 v7, 31, v6
	s_and_saveexec_b64 s[48:49], vcc
	s_cbranch_execz .LBB0_1323
	v_ashrrev_i32_e32 v9, 31, v8
	v_lshlrev_b64 v[74:75], 11, v[8:9]
	v_lshl_add_u64 v[74:75], s[18:19], 0, v[74:75]
	v_lshl_add_u64 v[74:75], v[6:7], 1, v[74:75]
	global_load_dwordx2 v[76:77], v[74:75], off
	global_load_dwordx2 v[100:101], v[74:75], off offset:32
	global_load_dwordx2 v[102:103], v[74:75], off offset:256
	global_load_dwordx2 v[104:105], v[74:75], off offset:288
	v_lshlrev_b64 v[78:79], 12, v[8:9]
	v_lshl_add_u64 v[78:79], s[12:13], 0, v[78:79]
	v_lshl_add_u64 v[78:79], v[6:7], 2, v[78:79]
	s_waitcnt vmcnt(3)
	s_nop 1
	v_and_b32_e32 v81, 0xffff0000, v77
	v_lshlrev_b32_e32 v80, 16, v77
	v_and_b32_e32 v77, 0xffff0000, v76
	v_lshlrev_b32_e32 v76, 16, v76
	v_pk_fma_f32 v[70:71], v[70:71], 0.5, v[76:77] op_sel_hi:[1,0,1]
	v_pk_fma_f32 v[72:73], v[72:73], 0.5, v[80:81] op_sel_hi:[1,0,1]
	global_store_dwordx4 v[78:79], v[70:73], off
	s_waitcnt vmcnt(3)
	s_nop 1
	v_and_b32_e32 v73, 0xffff0000, v101
	v_lshlrev_b32_e32 v72, 16, v101
	v_and_b32_e32 v71, 0xffff0000, v100
	v_lshlrev_b32_e32 v70, 16, v100
	v_pk_fma_f32 v[68:69], v[68:69], 0.5, v[70:71] op_sel_hi:[1,0,1]
	v_pk_fma_f32 v[70:71], v[66:67], 0.5, v[72:73] op_sel_hi:[1,0,1]
	global_store_dwordx4 v[78:79], v[68:71], off offset:64
	s_waitcnt vmcnt(3)
	s_nop 1
	v_and_b32_e32 v69, 0xffff0000, v103
	v_lshlrev_b32_e32 v68, 16, v103
	v_and_b32_e32 v67, 0xffff0000, v102
	v_lshlrev_b32_e32 v66, 16, v102
	v_pk_fma_f32 v[64:65], v[64:65], 0.5, v[66:67] op_sel_hi:[1,0,1]
	v_pk_fma_f32 v[66:67], v[62:63], 0.5, v[68:69] op_sel_hi:[1,0,1]
	global_store_dwordx4 v[78:79], v[64:67], off offset:512
	s_waitcnt vmcnt(3)
	s_nop 1
	v_and_b32_e32 v65, 0xffff0000, v105
	v_lshlrev_b32_e32 v64, 16, v105
	v_and_b32_e32 v63, 0xffff0000, v104
	v_lshlrev_b32_e32 v62, 16, v104
	v_pk_fma_f32 v[60:61], v[60:61], 0.5, v[62:63] op_sel_hi:[1,0,1]
	v_pk_fma_f32 v[62:63], v[58:59], 0.5, v[64:65] op_sel_hi:[1,0,1]
	global_store_dwordx4 v[78:79], v[60:63], off offset:576
;     __device__ __forceinline__ void operator()(const f32x4 (&acc)[2][2][4][2], const pg8::Unit& u, int wr, int wc, int fr, int fq) const {
;     ...
;             for (int m = 0; m < 4; ++m) { const int row = row0 + ai * 128 + m * 16;
;                 if (row < MV) {
;                     const float* rp = (row < MPR) ? res_p + (size_t)row * DM : res_s + (size_t)(row - MPR) * DM;
;                     float s = 0.f;
; #pragma unroll
;                     for (int bj = 0; bj < 2; ++bj)
; #pragma unroll
;                         for (int n = 0; n < 2; ++n) { const int col = col0 + bj * 128 + n * 16; f32x4 r;
;                             if (RESB) { const u32x2 rw = *(const u32x2*)(resb + (size_t)row * DM + col); r = (f32x4){bf2f(rw.x & 0xffff), bf2f(rw.x >> 16), bf2f(rw.y & 0xffff), bf2f(rw.y >> 16)}; }
;                             else r = *(const f32x4*)(rp + col);
;                             const f32x4 v = r + acc[ai][bj][m][n] * scale;
;                             if (OUTF) *(f32x4*)(out + (size_t)row * DM + col) = v;
.LBB0_1323:
	s_or_b64 exec, exec, s[48:49]
	s_waitcnt vmcnt(49)
	v_or_b32_e32 v58, 16, v8
	v_cmp_gt_i32_e32 vcc, s83, v58
	s_and_saveexec_b64 s[48:49], vcc
	s_cbranch_execz .LBB0_1325
	s_waitcnt vmcnt(48)
	v_ashrrev_i32_e32 v59, 31, v58
	v_lshlrev_b64 v[60:61], 11, v[58:59]
	v_lshl_add_u64 v[60:61], s[18:19], 0, v[60:61]
	v_lshl_add_u64 v[60:61], v[6:7], 1, v[60:61]
	global_load_dwordx2 v[62:63], v[60:61], off
	global_load_dwordx2 v[100:101], v[60:61], off offset:32
	global_load_dwordx2 v[102:103], v[60:61], off offset:256
	global_load_dwordx2 v[104:105], v[60:61], off offset:288
	v_lshlrev_b64 v[58:59], 12, v[58:59]
	v_lshl_add_u64 v[58:59], s[12:13], 0, v[58:59]
	v_lshl_add_u64 v[58:59], v[6:7], 2, v[58:59]
	s_waitcnt vmcnt(3)
	s_nop 1
	v_and_b32_e32 v65, 0xffff0000, v63
	v_lshlrev_b32_e32 v64, 16, v63
	v_and_b32_e32 v63, 0xffff0000, v62
	v_lshlrev_b32_e32 v62, 16, v62
	v_pk_fma_f32 v[54:55], v[54:55], 0.5, v[62:63] op_sel_hi:[1,0,1]
	v_pk_fma_f32 v[56:57], v[56:57], 0.5, v[64:65] op_sel_hi:[1,0,1]
	global_store_dwordx4 v[58:59], v[54:57], off
	s_waitcnt vmcnt(3)
	s_nop 1
	v_and_b32_e32 v57, 0xffff0000, v101
	v_lshlrev_b32_e32 v56, 16, v101
	v_and_b32_e32 v55, 0xffff0000, v100
	v_lshlrev_b32_e32 v54, 16, v100
	v_pk_fma_f32 v[52:53], v[52:53], 0.5, v[54:55] op_sel_hi:[1,0,1]
	v_pk_fma_f32 v[54:55], v[50:51], 0.5, v[56:57] op_sel_hi:[1,0,1]
	global_store_dwordx4 v[58:59], v[52:55], off offset:64
	s_waitcnt vmcnt(3)
	s_nop 1
	v_and_b32_e32 v53, 0xffff0000, v103
	v_lshlrev_b32_e32 v52, 16, v103
	v_and_b32_e32 v51, 0xffff0000, v102
	v_lshlrev_b32_e32 v50, 16, v102
	v_pk_fma_f32 v[48:49], v[48:49], 0.5, v[50:51] op_sel_hi:[1,0,1]
	v_pk_fma_f32 v[50:51], v[46:47], 0.5, v[52:53] op_sel_hi:[1,0,1]
	global_store_dwordx4 v[58:59], v[48:51], off offset:512
	s_waitcnt vmcnt(3)
	s_nop 1
	v_and_b32_e32 v49, 0xffff0000, v105
	v_lshlrev_b32_e32 v48, 16, v105
	v_and_b32_e32 v47, 0xffff0000, v104
	v_lshlrev_b32_e32 v46, 16, v104
	v_pk_fma_f32 v[44:45], v[44:45], 0.5, v[46:47] op_sel_hi:[1,0,1]
	v_pk_fma_f32 v[46:47], v[42:43], 0.5, v[48:49] op_sel_hi:[1,0,1]
	global_store_dwordx4 v[58:59], v[44:47], off offset:576
.LBB0_1325:
	s_or_b64 exec, exec, s[48:49]
	s_waitcnt vmcnt(33)
	v_or_b32_e32 v42, 32, v8
	v_cmp_gt_i32_e32 vcc, s83, v42
	s_and_saveexec_b64 s[48:49], vcc
	s_cbranch_execz .LBB0_1327
	s_waitcnt vmcnt(32)
	v_ashrrev_i32_e32 v43, 31, v42
	v_lshlrev_b64 v[44:45], 11, v[42:43]
	v_lshl_add_u64 v[44:45], s[18:19], 0, v[44:45]
	v_lshl_add_u64 v[44:45], v[6:7], 1, v[44:45]
	global_load_dwordx2 v[46:47], v[44:45], off
	global_load_dwordx2 v[100:101], v[44:45], off offset:32
	global_load_dwordx2 v[102:103], v[44:45], off offset:256
	global_load_dwordx2 v[104:105], v[44:45], off offset:288
	v_lshlrev_b64 v[42:43], 12, v[42:43]
	v_lshl_add_u64 v[42:43], s[12:13], 0, v[42:43]
	v_lshl_add_u64 v[42:43], v[6:7], 2, v[42:43]
	s_waitcnt vmcnt(3)
	s_nop 1
	v_and_b32_e32 v49, 0xffff0000, v47
	v_lshlrev_b32_e32 v48, 16, v47
	v_and_b32_e32 v47, 0xffff0000, v46
	v_lshlrev_b32_e32 v46, 16, v46
	v_pk_fma_f32 v[38:39], v[38:39], 0.5, v[46:47] op_sel_hi:[1,0,1]
	v_pk_fma_f32 v[40:41], v[40:41], 0.5, v[48:49] op_sel_hi:[1,0,1]
	global_store_dwordx4 v[42:43], v[38:41], off
	s_waitcnt vmcnt(3)
	s_nop 1
	v_and_b32_e32 v41, 0xffff0000, v101
	v_lshlrev_b32_e32 v40, 16, v101
	v_and_b32_e32 v39, 0xffff0000, v100
	v_lshlrev_b32_e32 v38, 16, v100
	v_pk_fma_f32 v[36:37], v[36:37], 0.5, v[38:39] op_sel_hi:[1,0,1]
	v_pk_fma_f32 v[38:39], v[34:35], 0.5, v[40:41] op_sel_hi:[1,0,1]
	global_store_dwordx4 v[42:43], v[36:39], off offset:64
	s_waitcnt vmcnt(3)
	s_nop 1
	v_and_b32_e32 v37, 0xffff0000, v103
	v_lshlrev_b32_e32 v36, 16, v103
	v_and_b32_e32 v35, 0xffff0000, v102
	v_lshlrev_b32_e32 v34, 16, v102
	v_pk_fma_f32 v[32:33], v[32:33], 0.5, v[34:35] op_sel_hi:[1,0,1]
	v_pk_fma_f32 v[34:35], v[30:31], 0.5, v[36:37] op_sel_hi:[1,0,1]
	global_store_dwordx4 v[42:43], v[32:35], off offset:512
	s_waitcnt vmcnt(3)
	s_nop 1
	v_and_b32_e32 v33, 0xffff0000, v105
	v_lshlrev_b32_e32 v32, 16, v105
	v_and_b32_e32 v31, 0xffff0000, v104
	v_lshlrev_b32_e32 v30, 16, v104
	v_pk_fma_f32 v[28:29], v[28:29], 0.5, v[30:31] op_sel_hi:[1,0,1]
	v_pk_fma_f32 v[30:31], v[26:27], 0.5, v[32:33] op_sel_hi:[1,0,1]
	global_store_dwordx4 v[42:43], v[28:31], off offset:576
.LBB0_1327:
	s_or_b64 exec, exec, s[48:49]
	s_waitcnt vmcnt(17)
	v_or_b32_e32 v26, 48, v8
	v_cmp_gt_i32_e32 vcc, s83, v26
	s_and_saveexec_b64 s[48:49], vcc
	s_cbranch_execz .LBB0_1331
	s_waitcnt vmcnt(16)
	v_ashrrev_i32_e32 v27, 31, v26
	v_lshlrev_b64 v[28:29], 11, v[26:27]
	v_lshl_add_u64 v[28:29], s[18:19], 0, v[28:29]
	v_lshl_add_u64 v[28:29], v[6:7], 1, v[28:29]
	global_load_dwordx2 v[30:31], v[28:29], off
	global_load_dwordx2 v[100:101], v[28:29], off offset:32
	global_load_dwordx2 v[102:103], v[28:29], off offset:256
	global_load_dwordx2 v[104:105], v[28:29], off offset:288
	v_lshlrev_b64 v[26:27], 12, v[26:27]
	v_lshl_add_u64 v[26:27], s[12:13], 0, v[26:27]
	v_lshl_add_u64 v[26:27], v[6:7], 2, v[26:27]
	s_waitcnt vmcnt(3)
	s_nop 1
	v_and_b32_e32 v33, 0xffff0000, v31
	v_lshlrev_b32_e32 v32, 16, v31
	v_and_b32_e32 v31, 0xffff0000, v30
	v_lshlrev_b32_e32 v30, 16, v30
	v_pk_fma_f32 v[22:23], v[22:23], 0.5, v[30:31] op_sel_hi:[1,0,1]
	v_pk_fma_f32 v[24:25], v[24:25], 0.5, v[32:33] op_sel_hi:[1,0,1]
	global_store_dwordx4 v[26:27], v[22:25], off
	s_waitcnt vmcnt(3)
	s_nop 1
	v_and_b32_e32 v25, 0xffff0000, v101
	v_lshlrev_b32_e32 v24, 16, v101
	v_and_b32_e32 v23, 0xffff0000, v100
	v_lshlrev_b32_e32 v22, 16, v100
	v_pk_fma_f32 v[20:21], v[20:21], 0.5, v[22:23] op_sel_hi:[1,0,1]
	v_pk_fma_f32 v[22:23], v[18:19], 0.5, v[24:25] op_sel_hi:[1,0,1]
	global_store_dwordx4 v[26:27], v[20:23], off offset:64
	s_waitcnt vmcnt(3)
	s_nop 1
	v_and_b32_e32 v21, 0xffff0000, v103
	v_lshlrev_b32_e32 v20, 16, v103
	v_and_b32_e32 v19, 0xffff0000, v102
	v_lshlrev_b32_e32 v18, 16, v102
	v_pk_fma_f32 v[16:17], v[16:17], 0.5, v[18:19] op_sel_hi:[1,0,1]
	v_pk_fma_f32 v[18:19], v[14:15], 0.5, v[20:21] op_sel_hi:[1,0,1]
	global_store_dwordx4 v[26:27], v[16:19], off offset:512
	s_waitcnt vmcnt(3)
	s_nop 1
	v_and_b32_e32 v17, 0xffff0000, v105
	v_lshlrev_b32_e32 v16, 16, v105
	v_and_b32_e32 v15, 0xffff0000, v104
	v_lshlrev_b32_e32 v14, 16, v104
	v_pk_fma_f32 v[12:13], v[12:13], 0.5, v[14:15] op_sel_hi:[1,0,1]
	v_pk_fma_f32 v[14:15], v[10:11], 0.5, v[16:17] op_sel_hi:[1,0,1]
	global_store_dwordx4 v[26:27], v[12:15], off offset:576
	s_or_b64 exec, exec, s[48:49]
	v_cmp_gt_i32_e32 vcc, s80, v8
	s_and_saveexec_b64 s[48:49], vcc
	s_cbranch_execnz .LBB0_1332
